# P1 epilogue store addresses: 64x64-bit row*stride multiply (2 v_mul_lo_u32 + v_mad_u64_u32 + v_add3) replaced by one v_mul_u32_u24 (row < 2^24, stride 0x400/0x200), 16 sites
# baseline (speedup 1.0000x reference)
; DI unsigned pk2(float a, float b) { f32x2 v = {a, b}; return __builtin_bit_cast(unsigned, __builtin_convertvector(v, bfv2)); }
;     DI void operator()(const pg8::f32x4 (&acc)[2][2][4][2], const pg8::Unit& u, int wr, int wc, int fr, int fq) const {
;     ...
;                         bf16_t* dst; int ld;
;                         switch (split) {
;                             case 0: dst = (bf16_t*)(dout + DO_AQ); ld = 1024; break;
;                             case 1: dst = (bf16_t*)(ws + OFF_AK); ld = 1024; break;
;                             case 3: dst = (bf16_t*)(ws + OFF_AZ); ld = 1024; break;
;                             case 4: dst = (bf16_t*)(dout + DO_GQ); ld = 512; break;
;                             case 5: dst = (bf16_t*)(dout + DO_GK); ld = 512; break;
;                             default: dst = (bf16_t*)(ws + OFF_GZ); ld = 1024; break;
;                         }
;                         u32x4 o; o.x = pk2(v[0], v[1]); o.y = pk2(v[2], v[3]); o.z = pk2(v[4], v[5]); o.w = pk2(v[6], v[7]);
;                         *(u32x4*)(dst + (size_t)tok * ld + nb) = o;
.LBB0_365:
	v_cvt_pk_bf16_f32 v8, v8, v9
	v_cvt_pk_bf16_f32 v9, v10, v11
	v_cvt_pk_bf16_f32 v10, v12, v13
	v_cvt_pk_bf16_f32 v11, v14, v15
	v_mul_u32_u24_e32 v12, s80, v158
	v_mov_b32_e32 v13, 0
	v_lshl_add_u64 v[12:13], v[12:13], 1, s[78:79]
	v_ashrrev_i32_e32 v137, 31, v136
	v_lshl_add_u64 v[12:13], v[136:137], 1, v[12:13]
	global_store_dwordx4 v[12:13], v[8:11], off
	s_mov_b64 s[6:7], 0

; DI unsigned pk2(float a, float b) { f32x2 v = {a, b}; return __builtin_bit_cast(unsigned, __builtin_convertvector(v, bfv2)); }
;     DI void operator()(const pg8::f32x4 (&acc)[2][2][4][2], const pg8::Unit& u, int wr, int wc, int fr, int fq) const {
;     ...
;                         bf16_t* dst; int ld;
;                         switch (split) {
;                             case 0: dst = (bf16_t*)(dout + DO_AQ); ld = 1024; break;
;                             case 1: dst = (bf16_t*)(ws + OFF_AK); ld = 1024; break;
;                             case 3: dst = (bf16_t*)(ws + OFF_AZ); ld = 1024; break;
;                             case 4: dst = (bf16_t*)(dout + DO_GQ); ld = 512; break;
;                             case 5: dst = (bf16_t*)(dout + DO_GK); ld = 512; break;
;                             default: dst = (bf16_t*)(ws + OFF_GZ); ld = 1024; break;
;                         }
;                         u32x4 o; o.x = pk2(v[0], v[1]); o.y = pk2(v[2], v[3]); o.z = pk2(v[4], v[5]); o.w = pk2(v[6], v[7]);
;                         *(u32x4*)(dst + (size_t)tok * ld + nb) = o;
.LBB0_437:
	v_cvt_pk_bf16_f32 v8, v8, v9
	v_cvt_pk_bf16_f32 v9, v10, v11
	v_cvt_pk_bf16_f32 v10, v12, v13
	v_cvt_pk_bf16_f32 v11, v14, v15
	v_mul_u32_u24_e32 v12, s80, v158
	v_mov_b32_e32 v13, 0
	v_lshl_add_u64 v[12:13], v[12:13], 1, s[78:79]
	v_ashrrev_i32_e32 v137, 31, v136
	v_lshl_add_u64 v[12:13], v[136:137], 1, v[12:13]
	global_store_dwordx4 v[12:13], v[8:11], off offset:256
	s_mov_b64 s[58:59], 0

; DI unsigned pk2(float a, float b) { f32x2 v = {a, b}; return __builtin_bit_cast(unsigned, __builtin_convertvector(v, bfv2)); }
;     DI void operator()(const pg8::f32x4 (&acc)[2][2][4][2], const pg8::Unit& u, int wr, int wc, int fr, int fq) const {
;     ...
;                         bf16_t* dst; int ld;
;                         switch (split) {
;                             case 0: dst = (bf16_t*)(dout + DO_AQ); ld = 1024; break;
;                             case 1: dst = (bf16_t*)(ws + OFF_AK); ld = 1024; break;
;                             case 3: dst = (bf16_t*)(ws + OFF_AZ); ld = 1024; break;
;                             case 4: dst = (bf16_t*)(dout + DO_GQ); ld = 512; break;
;                             case 5: dst = (bf16_t*)(dout + DO_GK); ld = 512; break;
;                             default: dst = (bf16_t*)(ws + OFF_GZ); ld = 1024; break;
;                         }
;                         u32x4 o; o.x = pk2(v[0], v[1]); o.y = pk2(v[2], v[3]); o.z = pk2(v[4], v[5]); o.w = pk2(v[6], v[7]);
;                         *(u32x4*)(dst + (size_t)tok * ld + nb) = o;
.LBB0_509:
	v_cvt_pk_bf16_f32 v8, v8, v9
	v_cvt_pk_bf16_f32 v9, v10, v11
	v_cvt_pk_bf16_f32 v10, v12, v13
	v_cvt_pk_bf16_f32 v11, v14, v15
	v_mul_u32_u24_e32 v12, s80, v130
	v_mov_b32_e32 v13, 0
	v_lshl_add_u64 v[12:13], v[12:13], 1, s[78:79]
	v_ashrrev_i32_e32 v137, 31, v136
	v_lshl_add_u64 v[12:13], v[136:137], 1, v[12:13]
	global_store_dwordx4 v[12:13], v[8:11], off
	s_mov_b64 s[58:59], 0

; DI unsigned pk2(float a, float b) { f32x2 v = {a, b}; return __builtin_bit_cast(unsigned, __builtin_convertvector(v, bfv2)); }
;     DI void operator()(const pg8::f32x4 (&acc)[2][2][4][2], const pg8::Unit& u, int wr, int wc, int fr, int fq) const {
;     ...
;                         bf16_t* dst; int ld;
;                         switch (split) {
;                             case 0: dst = (bf16_t*)(dout + DO_AQ); ld = 1024; break;
;                             case 1: dst = (bf16_t*)(ws + OFF_AK); ld = 1024; break;
;                             case 3: dst = (bf16_t*)(ws + OFF_AZ); ld = 1024; break;
;                             case 4: dst = (bf16_t*)(dout + DO_GQ); ld = 512; break;
;                             case 5: dst = (bf16_t*)(dout + DO_GK); ld = 512; break;
;                             default: dst = (bf16_t*)(ws + OFF_GZ); ld = 1024; break;
;                         }
;                         u32x4 o; o.x = pk2(v[0], v[1]); o.y = pk2(v[2], v[3]); o.z = pk2(v[4], v[5]); o.w = pk2(v[6], v[7]);
;                         *(u32x4*)(dst + (size_t)tok * ld + nb) = o;
.LBB0_643:
	v_cvt_pk_bf16_f32 v8, v8, v9
	v_cvt_pk_bf16_f32 v9, v10, v11
	v_cvt_pk_bf16_f32 v10, v12, v13
	v_cvt_pk_bf16_f32 v11, v14, v15
	v_mul_u32_u24_e32 v12, s80, v130
	v_mov_b32_e32 v13, 0
	v_lshl_add_u64 v[12:13], v[12:13], 1, s[78:79]
	v_ashrrev_i32_e32 v137, 31, v136
	v_lshl_add_u64 v[12:13], v[136:137], 1, v[12:13]
	global_store_dwordx4 v[12:13], v[8:11], off offset:256
	s_mov_b64 s[58:59], 0

; DI unsigned pk2(float a, float b) { f32x2 v = {a, b}; return __builtin_bit_cast(unsigned, __builtin_convertvector(v, bfv2)); }
;     DI void operator()(const pg8::f32x4 (&acc)[2][2][4][2], const pg8::Unit& u, int wr, int wc, int fr, int fq) const {
;     ...
;                         bf16_t* dst; int ld;
;                         switch (split) {
;                             case 0: dst = (bf16_t*)(dout + DO_AQ); ld = 1024; break;
;                             case 1: dst = (bf16_t*)(ws + OFF_AK); ld = 1024; break;
;                             case 3: dst = (bf16_t*)(ws + OFF_AZ); ld = 1024; break;
;                             case 4: dst = (bf16_t*)(dout + DO_GQ); ld = 512; break;
;                             case 5: dst = (bf16_t*)(dout + DO_GK); ld = 512; break;
;                             default: dst = (bf16_t*)(ws + OFF_GZ); ld = 1024; break;
;                         }
;                         u32x4 o; o.x = pk2(v[0], v[1]); o.y = pk2(v[2], v[3]); o.z = pk2(v[4], v[5]); o.w = pk2(v[6], v[7]);
;                         *(u32x4*)(dst + (size_t)tok * ld + nb) = o;
.LBB0_653:
	v_cvt_pk_bf16_f32 v8, v8, v9
	v_cvt_pk_bf16_f32 v9, v10, v11
	v_cvt_pk_bf16_f32 v10, v12, v13
	v_cvt_pk_bf16_f32 v11, v14, v15
	v_mul_u32_u24_e32 v12, s80, v112
	v_mov_b32_e32 v13, 0
	v_lshl_add_u64 v[12:13], v[12:13], 1, s[78:79]
	v_ashrrev_i32_e32 v137, 31, v136
	v_lshl_add_u64 v[12:13], v[136:137], 1, v[12:13]
	global_store_dwordx4 v[12:13], v[8:11], off
	s_mov_b64 s[58:59], 0

; DI unsigned pk2(float a, float b) { f32x2 v = {a, b}; return __builtin_bit_cast(unsigned, __builtin_convertvector(v, bfv2)); }
;     DI void operator()(const pg8::f32x4 (&acc)[2][2][4][2], const pg8::Unit& u, int wr, int wc, int fr, int fq) const {
;     ...
;                         bf16_t* dst; int ld;
;                         switch (split) {
;                             case 0: dst = (bf16_t*)(dout + DO_AQ); ld = 1024; break;
;                             case 1: dst = (bf16_t*)(ws + OFF_AK); ld = 1024; break;
;                             case 3: dst = (bf16_t*)(ws + OFF_AZ); ld = 1024; break;
;                             case 4: dst = (bf16_t*)(dout + DO_GQ); ld = 512; break;
;                             case 5: dst = (bf16_t*)(dout + DO_GK); ld = 512; break;
;                             default: dst = (bf16_t*)(ws + OFF_GZ); ld = 1024; break;
;                         }
;                         u32x4 o; o.x = pk2(v[0], v[1]); o.y = pk2(v[2], v[3]); o.z = pk2(v[4], v[5]); o.w = pk2(v[6], v[7]);
;                         *(u32x4*)(dst + (size_t)tok * ld + nb) = o;
.LBB0_787:
	v_cvt_pk_bf16_f32 v8, v8, v9
	v_cvt_pk_bf16_f32 v9, v10, v11
	v_cvt_pk_bf16_f32 v10, v12, v13
	v_cvt_pk_bf16_f32 v11, v14, v15
	v_mul_u32_u24_e32 v12, s80, v112
	v_mov_b32_e32 v13, 0
	v_lshl_add_u64 v[12:13], v[12:13], 1, s[78:79]
	v_ashrrev_i32_e32 v137, 31, v136
	v_lshl_add_u64 v[12:13], v[136:137], 1, v[12:13]
	global_store_dwordx4 v[12:13], v[8:11], off offset:256
	s_mov_b64 s[58:59], 0

; DI unsigned pk2(float a, float b) { f32x2 v = {a, b}; return __builtin_bit_cast(unsigned, __builtin_convertvector(v, bfv2)); }
;     DI void operator()(const pg8::f32x4 (&acc)[2][2][4][2], const pg8::Unit& u, int wr, int wc, int fr, int fq) const {
;     ...
;                         bf16_t* dst; int ld;
;                         switch (split) {
;                             case 0: dst = (bf16_t*)(dout + DO_AQ); ld = 1024; break;
;                             case 1: dst = (bf16_t*)(ws + OFF_AK); ld = 1024; break;
;                             case 3: dst = (bf16_t*)(ws + OFF_AZ); ld = 1024; break;
;                             case 4: dst = (bf16_t*)(dout + DO_GQ); ld = 512; break;
;                             case 5: dst = (bf16_t*)(dout + DO_GK); ld = 512; break;
;                             default: dst = (bf16_t*)(ws + OFF_GZ); ld = 1024; break;
;                         }
;                         u32x4 o; o.x = pk2(v[0], v[1]); o.y = pk2(v[2], v[3]); o.z = pk2(v[4], v[5]); o.w = pk2(v[6], v[7]);
;                         *(u32x4*)(dst + (size_t)tok * ld + nb) = o;
.LBB0_797:
	v_cvt_pk_bf16_f32 v8, v8, v9
	v_cvt_pk_bf16_f32 v9, v10, v11
	v_cvt_pk_bf16_f32 v10, v12, v13
	v_cvt_pk_bf16_f32 v11, v14, v15
	v_mul_u32_u24_e32 v12, s80, v96
	v_mov_b32_e32 v13, 0
	v_lshl_add_u64 v[12:13], v[12:13], 1, s[78:79]
	v_ashrrev_i32_e32 v137, 31, v136
	v_lshl_add_u64 v[12:13], v[136:137], 1, v[12:13]
	global_store_dwordx4 v[12:13], v[8:11], off
	s_mov_b64 s[58:59], 0

; DI unsigned pk2(float a, float b) { f32x2 v = {a, b}; return __builtin_bit_cast(unsigned, __builtin_convertvector(v, bfv2)); }
;     DI void operator()(const pg8::f32x4 (&acc)[2][2][4][2], const pg8::Unit& u, int wr, int wc, int fr, int fq) const {
;     ...
;                         bf16_t* dst; int ld;
;                         switch (split) {
;                             case 0: dst = (bf16_t*)(dout + DO_AQ); ld = 1024; break;
;                             case 1: dst = (bf16_t*)(ws + OFF_AK); ld = 1024; break;
;                             case 3: dst = (bf16_t*)(ws + OFF_AZ); ld = 1024; break;
;                             case 4: dst = (bf16_t*)(dout + DO_GQ); ld = 512; break;
;                             case 5: dst = (bf16_t*)(dout + DO_GK); ld = 512; break;
;                             default: dst = (bf16_t*)(ws + OFF_GZ); ld = 1024; break;
;                         }
;                         u32x4 o; o.x = pk2(v[0], v[1]); o.y = pk2(v[2], v[3]); o.z = pk2(v[4], v[5]); o.w = pk2(v[6], v[7]);
;                         *(u32x4*)(dst + (size_t)tok * ld + nb) = o;
.LBB0_931:
	v_cvt_pk_bf16_f32 v8, v8, v9
	v_cvt_pk_bf16_f32 v9, v10, v11
	v_cvt_pk_bf16_f32 v10, v12, v13
	v_cvt_pk_bf16_f32 v11, v14, v15
	v_mul_u32_u24_e32 v12, s80, v96
	v_mov_b32_e32 v13, 0
	v_lshl_add_u64 v[12:13], v[12:13], 1, s[78:79]
	v_ashrrev_i32_e32 v137, 31, v136
	v_lshl_add_u64 v[12:13], v[136:137], 1, v[12:13]
	global_store_dwordx4 v[12:13], v[8:11], off offset:256
	s_mov_b64 s[58:59], 0

; DI unsigned pk2(float a, float b) { f32x2 v = {a, b}; return __builtin_bit_cast(unsigned, __builtin_convertvector(v, bfv2)); }
;     DI void operator()(const pg8::f32x4 (&acc)[2][2][4][2], const pg8::Unit& u, int wr, int wc, int fr, int fq) const {
;     ...
;                         bf16_t* dst; int ld;
;                         switch (split) {
;                             case 0: dst = (bf16_t*)(dout + DO_AQ); ld = 1024; break;
;                             case 1: dst = (bf16_t*)(ws + OFF_AK); ld = 1024; break;
;                             case 3: dst = (bf16_t*)(ws + OFF_AZ); ld = 1024; break;
;                             case 4: dst = (bf16_t*)(dout + DO_GQ); ld = 512; break;
;                             case 5: dst = (bf16_t*)(dout + DO_GK); ld = 512; break;
;                             default: dst = (bf16_t*)(ws + OFF_GZ); ld = 1024; break;
;                         }
;                         u32x4 o; o.x = pk2(v[0], v[1]); o.y = pk2(v[2], v[3]); o.z = pk2(v[4], v[5]); o.w = pk2(v[6], v[7]);
;                         *(u32x4*)(dst + (size_t)tok * ld + nb) = o;
.LBB0_941:
	v_cvt_pk_bf16_f32 v8, v8, v9
	v_cvt_pk_bf16_f32 v9, v10, v11
	v_cvt_pk_bf16_f32 v10, v12, v13
	v_cvt_pk_bf16_f32 v11, v14, v15
	v_mul_u32_u24_e32 v12, s80, v80
	v_mov_b32_e32 v13, 0
	v_lshl_add_u64 v[12:13], v[12:13], 1, s[78:79]
	v_ashrrev_i32_e32 v137, 31, v136
	v_lshl_add_u64 v[12:13], v[136:137], 1, v[12:13]
	global_store_dwordx4 v[12:13], v[8:11], off
	s_mov_b64 s[58:59], 0

; DI unsigned pk2(float a, float b) { f32x2 v = {a, b}; return __builtin_bit_cast(unsigned, __builtin_convertvector(v, bfv2)); }
;     DI void operator()(const pg8::f32x4 (&acc)[2][2][4][2], const pg8::Unit& u, int wr, int wc, int fr, int fq) const {
;     ...
;                         bf16_t* dst; int ld;
;                         switch (split) {
;                             case 0: dst = (bf16_t*)(dout + DO_AQ); ld = 1024; break;
;                             case 1: dst = (bf16_t*)(ws + OFF_AK); ld = 1024; break;
;                             case 3: dst = (bf16_t*)(ws + OFF_AZ); ld = 1024; break;
;                             case 4: dst = (bf16_t*)(dout + DO_GQ); ld = 512; break;
;                             case 5: dst = (bf16_t*)(dout + DO_GK); ld = 512; break;
;                             default: dst = (bf16_t*)(ws + OFF_GZ); ld = 1024; break;
;                         }
;                         u32x4 o; o.x = pk2(v[0], v[1]); o.y = pk2(v[2], v[3]); o.z = pk2(v[4], v[5]); o.w = pk2(v[6], v[7]);
;                         *(u32x4*)(dst + (size_t)tok * ld + nb) = o;
.LBB0_1075:
	v_cvt_pk_bf16_f32 v8, v8, v9
	v_cvt_pk_bf16_f32 v9, v10, v11
	v_cvt_pk_bf16_f32 v10, v12, v13
	v_cvt_pk_bf16_f32 v11, v14, v15
	v_mul_u32_u24_e32 v12, s80, v80
	v_mov_b32_e32 v13, 0
	v_lshl_add_u64 v[12:13], v[12:13], 1, s[78:79]
	v_ashrrev_i32_e32 v137, 31, v136
	v_lshl_add_u64 v[12:13], v[136:137], 1, v[12:13]
	global_store_dwordx4 v[12:13], v[8:11], off offset:256
	s_mov_b64 s[58:59], 0

; DI unsigned pk2(float a, float b) { f32x2 v = {a, b}; return __builtin_bit_cast(unsigned, __builtin_convertvector(v, bfv2)); }
;     DI void operator()(const pg8::f32x4 (&acc)[2][2][4][2], const pg8::Unit& u, int wr, int wc, int fr, int fq) const {
;     ...
;                         bf16_t* dst; int ld;
;                         switch (split) {
;                             case 0: dst = (bf16_t*)(dout + DO_AQ); ld = 1024; break;
;                             case 1: dst = (bf16_t*)(ws + OFF_AK); ld = 1024; break;
;                             case 3: dst = (bf16_t*)(ws + OFF_AZ); ld = 1024; break;
;                             case 4: dst = (bf16_t*)(dout + DO_GQ); ld = 512; break;
;                             case 5: dst = (bf16_t*)(dout + DO_GK); ld = 512; break;
;                             default: dst = (bf16_t*)(ws + OFF_GZ); ld = 1024; break;
;                         }
;                         u32x4 o; o.x = pk2(v[0], v[1]); o.y = pk2(v[2], v[3]); o.z = pk2(v[4], v[5]); o.w = pk2(v[6], v[7]);
;                         *(u32x4*)(dst + (size_t)tok * ld + nb) = o;
.LBB0_1085:
	v_cvt_pk_bf16_f32 v8, v8, v9
	v_cvt_pk_bf16_f32 v9, v10, v11
	v_cvt_pk_bf16_f32 v10, v12, v13
	v_cvt_pk_bf16_f32 v11, v14, v15
	v_mul_u32_u24_e32 v12, s80, v64
	v_mov_b32_e32 v13, 0
	v_lshl_add_u64 v[12:13], v[12:13], 1, s[78:79]
	v_ashrrev_i32_e32 v137, 31, v136
	v_lshl_add_u64 v[12:13], v[136:137], 1, v[12:13]
	global_store_dwordx4 v[12:13], v[8:11], off
	s_mov_b64 s[58:59], 0

; DI unsigned pk2(float a, float b) { f32x2 v = {a, b}; return __builtin_bit_cast(unsigned, __builtin_convertvector(v, bfv2)); }
;     DI void operator()(const pg8::f32x4 (&acc)[2][2][4][2], const pg8::Unit& u, int wr, int wc, int fr, int fq) const {
;     ...
;                         bf16_t* dst; int ld;
;                         switch (split) {
;                             case 0: dst = (bf16_t*)(dout + DO_AQ); ld = 1024; break;
;                             case 1: dst = (bf16_t*)(ws + OFF_AK); ld = 1024; break;
;                             case 3: dst = (bf16_t*)(ws + OFF_AZ); ld = 1024; break;
;                             case 4: dst = (bf16_t*)(dout + DO_GQ); ld = 512; break;
;                             case 5: dst = (bf16_t*)(dout + DO_GK); ld = 512; break;
;                             default: dst = (bf16_t*)(ws + OFF_GZ); ld = 1024; break;
;                         }
;                         u32x4 o; o.x = pk2(v[0], v[1]); o.y = pk2(v[2], v[3]); o.z = pk2(v[4], v[5]); o.w = pk2(v[6], v[7]);
;                         *(u32x4*)(dst + (size_t)tok * ld + nb) = o;
.LBB0_1219:
	v_cvt_pk_bf16_f32 v8, v8, v9
	v_cvt_pk_bf16_f32 v9, v10, v11
	v_cvt_pk_bf16_f32 v10, v12, v13
	v_cvt_pk_bf16_f32 v11, v14, v15
	v_mul_u32_u24_e32 v12, s80, v64
	v_mov_b32_e32 v13, 0
	v_lshl_add_u64 v[12:13], v[12:13], 1, s[78:79]
	v_ashrrev_i32_e32 v137, 31, v136
	v_lshl_add_u64 v[12:13], v[136:137], 1, v[12:13]
	global_store_dwordx4 v[12:13], v[8:11], off offset:256
	s_mov_b64 s[58:59], 0

; DI unsigned pk2(float a, float b) { f32x2 v = {a, b}; return __builtin_bit_cast(unsigned, __builtin_convertvector(v, bfv2)); }
;     DI void operator()(const pg8::f32x4 (&acc)[2][2][4][2], const pg8::Unit& u, int wr, int wc, int fr, int fq) const {
;     ...
;                         bf16_t* dst; int ld;
;                         switch (split) {
;                             case 0: dst = (bf16_t*)(dout + DO_AQ); ld = 1024; break;
;                             case 1: dst = (bf16_t*)(ws + OFF_AK); ld = 1024; break;
;                             case 3: dst = (bf16_t*)(ws + OFF_AZ); ld = 1024; break;
;                             case 4: dst = (bf16_t*)(dout + DO_GQ); ld = 512; break;
;                             case 5: dst = (bf16_t*)(dout + DO_GK); ld = 512; break;
;                             default: dst = (bf16_t*)(ws + OFF_GZ); ld = 1024; break;
;                         }
;                         u32x4 o; o.x = pk2(v[0], v[1]); o.y = pk2(v[2], v[3]); o.z = pk2(v[4], v[5]); o.w = pk2(v[6], v[7]);
;                         *(u32x4*)(dst + (size_t)tok * ld + nb) = o;
.LBB0_1229:
	v_cvt_pk_bf16_f32 v8, v8, v9
	v_cvt_pk_bf16_f32 v9, v10, v11
	v_cvt_pk_bf16_f32 v10, v12, v13
	v_cvt_pk_bf16_f32 v11, v14, v15
	v_mul_u32_u24_e32 v12, s80, v48
	v_mov_b32_e32 v13, 0
	v_lshl_add_u64 v[12:13], v[12:13], 1, s[78:79]
	v_ashrrev_i32_e32 v137, 31, v136
	v_lshl_add_u64 v[12:13], v[136:137], 1, v[12:13]
	global_store_dwordx4 v[12:13], v[8:11], off
	s_mov_b64 s[58:59], 0

; DI unsigned pk2(float a, float b) { f32x2 v = {a, b}; return __builtin_bit_cast(unsigned, __builtin_convertvector(v, bfv2)); }
;     DI void operator()(const pg8::f32x4 (&acc)[2][2][4][2], const pg8::Unit& u, int wr, int wc, int fr, int fq) const {
;     ...
;                         bf16_t* dst; int ld;
;                         switch (split) {
;                             case 0: dst = (bf16_t*)(dout + DO_AQ); ld = 1024; break;
;                             case 1: dst = (bf16_t*)(ws + OFF_AK); ld = 1024; break;
;                             case 3: dst = (bf16_t*)(ws + OFF_AZ); ld = 1024; break;
;                             case 4: dst = (bf16_t*)(dout + DO_GQ); ld = 512; break;
;                             case 5: dst = (bf16_t*)(dout + DO_GK); ld = 512; break;
;                             default: dst = (bf16_t*)(ws + OFF_GZ); ld = 1024; break;
;                         }
;                         u32x4 o; o.x = pk2(v[0], v[1]); o.y = pk2(v[2], v[3]); o.z = pk2(v[4], v[5]); o.w = pk2(v[6], v[7]);
;                         *(u32x4*)(dst + (size_t)tok * ld + nb) = o;
.LBB0_1363:
	v_cvt_pk_bf16_f32 v8, v8, v9
	v_cvt_pk_bf16_f32 v9, v10, v11
	v_cvt_pk_bf16_f32 v10, v12, v13
	v_cvt_pk_bf16_f32 v11, v14, v15
	v_mul_u32_u24_e32 v12, s80, v48
	v_mov_b32_e32 v13, 0
	v_lshl_add_u64 v[12:13], v[12:13], 1, s[78:79]
	v_ashrrev_i32_e32 v137, 31, v136
	v_lshl_add_u64 v[12:13], v[136:137], 1, v[12:13]
	global_store_dwordx4 v[12:13], v[8:11], off offset:256
	s_mov_b64 s[58:59], 0

; DI unsigned pk2(float a, float b) { f32x2 v = {a, b}; return __builtin_bit_cast(unsigned, __builtin_convertvector(v, bfv2)); }
;     DI void operator()(const pg8::f32x4 (&acc)[2][2][4][2], const pg8::Unit& u, int wr, int wc, int fr, int fq) const {
;     ...
;                         bf16_t* dst; int ld;
;                         switch (split) {
;                             case 0: dst = (bf16_t*)(dout + DO_AQ); ld = 1024; break;
;                             case 1: dst = (bf16_t*)(ws + OFF_AK); ld = 1024; break;
;                             case 3: dst = (bf16_t*)(ws + OFF_AZ); ld = 1024; break;
;                             case 4: dst = (bf16_t*)(dout + DO_GQ); ld = 512; break;
;                             case 5: dst = (bf16_t*)(dout + DO_GK); ld = 512; break;
;                             default: dst = (bf16_t*)(ws + OFF_GZ); ld = 1024; break;
;                         }
;                         u32x4 o; o.x = pk2(v[0], v[1]); o.y = pk2(v[2], v[3]); o.z = pk2(v[4], v[5]); o.w = pk2(v[6], v[7]);
;                         *(u32x4*)(dst + (size_t)tok * ld + nb) = o;
.LBB0_1373:
	v_cvt_pk_bf16_f32 v8, v8, v9
	v_cvt_pk_bf16_f32 v9, v10, v11
	v_cvt_pk_bf16_f32 v10, v12, v13
	v_cvt_pk_bf16_f32 v11, v14, v15
	v_mul_u32_u24_e32 v12, s78, v32
	v_mov_b32_e32 v13, 0
	v_lshl_add_u64 v[12:13], v[12:13], 1, s[76:77]
	v_ashrrev_i32_e32 v137, 31, v136
	v_lshl_add_u64 v[12:13], v[136:137], 1, v[12:13]
	global_store_dwordx4 v[12:13], v[8:11], off
	s_mov_b64 s[10:11], 0

; DI unsigned pk2(float a, float b) { f32x2 v = {a, b}; return __builtin_bit_cast(unsigned, __builtin_convertvector(v, bfv2)); }
;     DI void operator()(const pg8::f32x4 (&acc)[2][2][4][2], const pg8::Unit& u, int wr, int wc, int fr, int fq) const {
;     ...
;                         bf16_t* dst; int ld;
;                         switch (split) {
;                             case 0: dst = (bf16_t*)(dout + DO_AQ); ld = 1024; break;
;                             case 1: dst = (bf16_t*)(ws + OFF_AK); ld = 1024; break;
;                             case 3: dst = (bf16_t*)(ws + OFF_AZ); ld = 1024; break;
;                             case 4: dst = (bf16_t*)(dout + DO_GQ); ld = 512; break;
;                             case 5: dst = (bf16_t*)(dout + DO_GK); ld = 512; break;
;                             default: dst = (bf16_t*)(ws + OFF_GZ); ld = 1024; break;
;                         }
;                         u32x4 o; o.x = pk2(v[0], v[1]); o.y = pk2(v[2], v[3]); o.z = pk2(v[4], v[5]); o.w = pk2(v[6], v[7]);
;                         *(u32x4*)(dst + (size_t)tok * ld + nb) = o;
.LBB0_1447:
	v_cvt_pk_bf16_f32 v8, v8, v9
	v_cvt_pk_bf16_f32 v9, v10, v11
	v_cvt_pk_bf16_f32 v10, v12, v13
	v_cvt_pk_bf16_f32 v11, v14, v15
	v_mul_u32_u24_e32 v12, s10, v32
	v_mov_b32_e32 v13, 0
	v_lshl_add_u64 v[12:13], v[12:13], 1, s[8:9]
	v_ashrrev_i32_e32 v137, 31, v136
	v_lshl_add_u64 v[12:13], v[136:137], 1, v[12:13]
	global_store_dwordx4 v[12:13], v[8:11], off offset:256
	s_mov_b64 s[4:5], 0
